# P1->GEMM1 seam XCD-local: phase-0 stores written through (sc0 sc1) and counted instead of an L2 writeback, P1 rows remapped to the consuming XCD, census resolved at P1 entry
# speedup vs baseline: 1.0234x; 1.0068x over previous
; __device__ __forceinline__ void phase0(const Ptrs& P, LAS unsigned char* lds, int G) {
;     ...
;           { const int b = tid >> 5, c2 = tid & 31; float sm = P.b_ada[n0 + c2];
; #pragma unroll
;             for (int w = 0; w < 8; ++w) sm += red[(w * 16 + b) * 32 + c2];
;             mod[b * 3072 + n0 + c2] = sm; }
.LBB0_30:
	s_or_b64 exec, exec, s[4:5]
	s_waitcnt lgkmcnt(0)
	v_or_b32_e32 v4, s2, v29
	v_ashrrev_i32_e32 v5, 31, v4
	v_lshl_add_u64 v[4:5], v[4:5], 2, s[56:57]
	s_barrier
	global_load_dword v14, v[4:5], off
	ds_read2st64_b32 v[4:5], v32 offset1:8
	ds_read2st64_b32 v[6:7], v32 offset0:16 offset1:24
	ds_read2st64_b32 v[8:9], v32 offset0:32 offset1:40
	ds_read2st64_b32 v[10:11], v32 offset0:48 offset1:56
	v_add_u32_e32 v12, s2, v33
	s_add_i32 s7, s7, s83
	v_ashrrev_i32_e32 v13, 31, v12
	s_cmpk_lt_i32 s7, 0x60
	v_lshl_add_u64 v[12:13], v[12:13], 2, s[0:1]
	s_waitcnt vmcnt(0) lgkmcnt(3)
	v_add_f32_e32 v4, v14, v4
	v_add_f32_e32 v4, v4, v5
	s_waitcnt lgkmcnt(2)
	v_add_f32_e32 v4, v4, v6
	v_add_f32_e32 v4, v4, v7
	s_waitcnt lgkmcnt(1)
	v_add_f32_e32 v4, v4, v8
	v_add_f32_e32 v4, v4, v9
	s_waitcnt lgkmcnt(0)
	v_add_f32_e32 v4, v4, v10
	v_add_f32_e32 v4, v4, v11
	global_store_dword v[12:13], v4, off sc0 sc1
	s_barrier
	s_cbranch_scc0 .LBB0_65

; __device__ __forceinline__ void phase0(const Ptrs& P, LAS unsigned char* lds, int G) {
;     ...
;     float* ssq = (float*)(P.ws + WS_SSQ);
;     for (int i = gt; i < 3 * T; i += NGT) ssq[i] = 0.f;
.LBB0_72:
	v_add_u32_e32 v7, -2, v7
	v_ashrrev_i32_e32 v9, 31, v3
	v_mov_b32_e32 v8, v3
	v_ashrrev_i32_e32 v11, 31, v2
	v_mov_b32_e32 v10, v2
	v_cmp_eq_u32_e32 vcc, 0, v7
	v_add_u32_e32 v3, s8, v3
	v_add_u32_e32 v2, s3, v2
	v_lshl_add_u64 v[10:11], v[10:11], 2, s[90:91]
	v_lshl_add_u64 v[8:9], v[8:9], 2, s[90:91]
	s_or_b64 s[6:7], vcc, s[6:7]
	global_store_dword v[10:11], v6, off sc0 sc1
	global_store_dword v[8:9], v6, off sc0 sc1
	s_andn2_b64 exec, exec, s[6:7]
	s_cbranch_execnz .LBB0_72
	s_or_b64 exec, exec, s[6:7]
	v_mad_u64_u32 v[2:3], s[6:7], v5, s2, v[0:1]
	v_cmp_ne_u32_e32 vcc, v4, v5
	s_orn2_b64 s[6:7], vcc, exec

; __device__ __forceinline__ void phase0(const Ptrs& P, LAS unsigned char* lds, int G) {
;     ...
;     float* ssq = (float*)(P.ws + WS_SSQ);
;     for (int i = gt; i < 3 * T; i += NGT) ssq[i] = 0.f;
.LBB0_76:
	v_add_u32_e32 v2, s2, v2
	v_cmp_lt_i32_e32 vcc, s3, v2
	global_store_dword v[4:5], v1, off sc0 sc1
	s_or_b64 s[6:7], vcc, s[6:7]
	v_lshl_add_u64 v[4:5], v[4:5], 0, s[0:1]
	s_andn2_b64 exec, exec, s[6:7]
	s_cbranch_execnz .LBB0_76

; __device__ __forceinline__ void phase0(const Ptrs& P, LAS unsigned char* lds, int G) {
;     ...
;     { float* rope = (float*)(P.ws + WS_ROPE);
;       for (int i = gt; i < T * 32; i += NGT) { const int row = i >> 5, j = i & 31;
;           const float inv = exp2f(-(float)j * (13.287712379549449f / 32.0f));
;           const float ang = (float)P.positions[row] * inv;
;           const double rev = (double)ang * 0.15915494309189535; const float fr = (float)(rev - rint(rev));
;           float sn, cs; { const float a = fr * 6.283185307179586f; sn = __sinf(a); cs = __cosf(a); }
;           *(f32x2_t*)(rope + (size_t)i * 2) = (f32x2_t){cs, sn}; } }
.LBB0_79:
	v_ashrrev_i32_e32 v6, 5, v0
	v_ashrrev_i32_e32 v7, 31, v6
	v_lshl_add_u64 v[6:7], v[6:7], 2, s[52:53]
	global_load_dword v1, v[6:7], off
	v_add_u32_e32 v0, s2, v0
	v_cmp_lt_i32_e32 vcc, s3, v0
	s_or_b64 s[6:7], vcc, s[6:7]
	s_waitcnt vmcnt(0)
	v_cvt_f32_i32_e32 v1, v1
	v_mul_f32_e32 v1, v4, v1
	v_cvt_f64_f32_e32 v[6:7], v1
	v_mul_f64 v[8:9], v[6:7], s[8:9]
	v_rndne_f64_e32 v[8:9], v[8:9]
	v_fma_f64 v[6:7], v[6:7], s[8:9], -v[8:9]
	v_cvt_f32_f64_e32 v1, v[6:7]
	v_mul_f32_e32 v1, 0x40c90fdb, v1
	v_mul_f32_e32 v1, 0.15915494, v1
	v_sin_f32_e32 v7, v1
	v_cos_f32_e32 v6, v1
	global_store_dwordx2 v[2:3], v[6:7], off sc0 sc1
	v_lshl_add_u64 v[2:3], v[2:3], 0, s[4:5]
	s_andn2_b64 exec, exec, s[6:7]
	s_cbranch_execnz .LBB0_79

; #define LAS __attribute__((address_space(3)))
; __device__ __forceinline__ unsigned pk2(float lo, float hi) { f32x2_t v = {lo, hi}; bf16x2_t b = __builtin_convertvector(v, bf16x2_t); return __builtin_bit_cast(unsigned, b); }
; __device__ __forceinline__ void transpose_item(const float* W, int ldw, int k0, int srcn0, bf16_t* WT, int ldk, int dstrow0, int dstk0, const float* ksc, LAS float* scr, int lane) {
;     ...
;     for (int i = 0; i < 32; ++i) { const int kk = 2 * i + (lane >> 5); float v = tv[i]; if (srcn0 >= 0 && ksc) v *= ksc[k0 + kk];
;         scr[kk * 33 + (lane & 31)] = v; }
;     asm volatile("s_waitcnt lgkmcnt(0)" ::: "memory");
;     const int c = lane & 7;
; #pragma unroll
;     for (int j = 0; j < 4; ++j) { const int n = (lane >> 3) + 8 * j; const LAS float* s = scr + (8 * c) * 33 + n;
;         u32x4 o; o.x = pk2(s[0 * 33], s[1 * 33]); o.y = pk2(s[2 * 33], s[3 * 33]); o.z = pk2(s[4 * 33], s[5 * 33]); o.w = pk2(s[6 * 33], s[7 * 33]);
;         *(u32x4*)(WT + (size_t)(dstrow0 + n) * ldk + dstk0 + 8 * c) = o; }
;     asm volatile("s_waitcnt lgkmcnt(0)" ::: "memory");
.LBB0_83:
	s_waitcnt vmcnt(0)
	ds_write2_b32 v46, v26, v27 offset1:66
	ds_write2_b32 v46, v29, v28 offset0:132 offset1:198
	ds_write2_b32 v64, v31, v30 offset0:8 offset1:74
	ds_write2_b32 v64, v33, v32 offset0:140 offset1:206
	ds_write2_b32 v65, v35, v34 offset0:16 offset1:82
	ds_write2_b32 v65, v37, v36 offset0:148 offset1:214
	ds_write2_b32 v66, v39, v38 offset0:24 offset1:90
	ds_write2_b32 v66, v41, v40 offset0:156 offset1:222
	ds_write2_b32 v67, v43, v42 offset0:32 offset1:98
	ds_write2_b32 v67, v72, v71 offset0:164 offset1:230
	ds_write2_b32 v68, v74, v73 offset0:40 offset1:106
	ds_write2_b32 v68, v76, v75 offset0:172 offset1:238
	ds_write2_b32 v69, v78, v77 offset0:48 offset1:114
	ds_write2_b32 v69, v80, v79 offset0:180 offset1:246
	ds_write2_b32 v70, v82, v81 offset0:56 offset1:122
	ds_write2_b32 v70, v84, v83 offset0:188 offset1:254
	s_waitcnt lgkmcnt(0)
	ds_read2_b32 v[28:29], v48 offset0:33 offset1:41
	ds_read2_b32 v[30:31], v48 offset1:8
	ds_read2_b32 v[32:33], v48 offset0:66 offset1:74
	ds_read2_b32 v[34:35], v48 offset0:99 offset1:107
	ds_read2_b32 v[36:37], v48 offset0:132 offset1:140
	ds_read2_b32 v[38:39], v48 offset0:165 offset1:173
	ds_read2_b32 v[40:41], v48 offset0:198 offset1:206
	ds_read2_b32 v[42:43], v48 offset0:231 offset1:239
	s_mul_i32 s0, s33, 0xffffe100
	s_add_i32 s0, s0, s14
	v_add_u32_e32 v74, s0, v47
	s_ashr_i32 s9, s8, 31
	v_ashrrev_i32_e32 v75, 31, v74
	v_lshl_add_u64 v[72:73], s[8:9], 1, v[10:11]
	v_lshlrev_b64 v[76:77], 11, v[74:75]
	s_waitcnt lgkmcnt(6)
	v_cvt_pk_bf16_f32 v24, v30, v28
	s_waitcnt lgkmcnt(4)
	v_cvt_pk_bf16_f32 v25, v32, v34
	s_waitcnt lgkmcnt(2)
	v_cvt_pk_bf16_f32 v26, v36, v38
	s_waitcnt lgkmcnt(0)
	v_cvt_pk_bf16_f32 v27, v40, v42
	v_lshl_add_u64 v[76:77], v[72:73], 0, v[76:77]
	v_add_u32_e32 v28, 8, v74
	global_store_dwordx4 v[76:77], v[24:27], off sc0 sc1
	s_nop 1
	v_cvt_pk_bf16_f32 v24, v31, v29
	v_ashrrev_i32_e32 v29, 31, v28
	v_cvt_pk_bf16_f32 v25, v33, v35
	v_cvt_pk_bf16_f32 v26, v37, v39
	v_cvt_pk_bf16_f32 v27, v41, v43
	v_lshlrev_b64 v[28:29], 11, v[28:29]
	ds_read2_b32 v[30:31], v48 offset0:49 offset1:57
	ds_read2_b32 v[32:33], v48 offset0:16 offset1:24
	ds_read2_b32 v[34:35], v48 offset0:82 offset1:90
	ds_read2_b32 v[36:37], v48 offset0:115 offset1:123
	ds_read2_b32 v[38:39], v48 offset0:148 offset1:156
	ds_read2_b32 v[40:41], v48 offset0:181 offset1:189
	ds_read2_b32 v[42:43], v48 offset0:214 offset1:222
	ds_read2_b32 v[76:77], v48 offset0:247 offset1:255
	v_lshl_add_u64 v[28:29], v[72:73], 0, v[28:29]
	global_store_dwordx4 v[28:29], v[24:27], off sc0 sc1
	v_add_u32_e32 v28, 16, v74
	v_ashrrev_i32_e32 v29, 31, v28
	v_lshlrev_b64 v[28:29], 11, v[28:29]
	s_waitcnt lgkmcnt(6)
	v_cvt_pk_bf16_f32 v24, v32, v30
	s_waitcnt lgkmcnt(4)
	v_cvt_pk_bf16_f32 v25, v34, v36
	s_waitcnt lgkmcnt(2)
	v_cvt_pk_bf16_f32 v26, v38, v40
	s_waitcnt lgkmcnt(0)
	v_cvt_pk_bf16_f32 v27, v42, v76
	v_lshl_add_u64 v[28:29], v[72:73], 0, v[28:29]
	global_store_dwordx4 v[28:29], v[24:27], off sc0 sc1
	v_add_u32_e32 v28, 24, v74
	v_ashrrev_i32_e32 v29, 31, v28
	v_lshlrev_b64 v[28:29], 11, v[28:29]
	v_cvt_pk_bf16_f32 v24, v33, v31
	v_cvt_pk_bf16_f32 v25, v35, v37
	v_cvt_pk_bf16_f32 v26, v39, v41
	v_cvt_pk_bf16_f32 v27, v43, v77
	v_lshl_add_u64 v[28:29], v[72:73], 0, v[28:29]
	global_store_dwordx4 v[28:29], v[24:27], off sc0 sc1
	s_waitcnt lgkmcnt(0)

; __device__ __forceinline__ void transpose_item(const float* W, int ldw, int k0, int srcn0, bf16_t* WT, int ldk, int dstrow0, int dstk0, const float* ksc, LAS float* scr, int lane) {
;     float tv[32];
; #pragma unroll
;     for (int i = 0; i < 32; ++i) { const int kk = 2 * i + (lane >> 5); tv[i] = 0.f;
;         if (srcn0 >= 0) { tv[i] = __builtin_nontemporal_load(W + (size_t)(k0 + kk) * ldw + srcn0 + (lane & 31)); } }
; __device__ __forceinline__ void phase0(const Ptrs& P, LAS unsigned char* lds, int G) {
;     ...
;       for (int it = gw; it < NITEMS; it += NGW) {
;           int r = it;
;           if (r < I_IN) { const int kb = r / 248, vg = r % 248; transpose_item(P.w_in, NIN, kb * 64, win_src(vg), WIN, 1024, vg * 32, kb * 64, nullptr, scr, lane); continue; } r -= I_IN;
;           if (r < I_M) { const int kb = r >> 5, nb = r & 31; if (kb < 16) transpose_item(P.w_conv_out, 1024, kb * 64, nb * 32, WM, 2048, nb * 32, kb * 64, nullptr, scr, lane);
;                          else transpose_item(P.w_mla_out, 1024, (kb - 16) * 64, nb * 32, WM, 2048, nb * 32, kb * 64, nullptr, scr, lane); continue; } r -= I_M;
;           if (r < I_UQ) { const int kb = r / 48, vg = r % 48; transpose_item(P.w_uq, 1536, kb * 64, wuq_src(vg), WUQ, QLORA, vg * 32, kb * 64, P.g_q, scr, lane); continue; } r -= I_UQ;
;           if (r < I_UKV) { const int kb = r >> 6, vg = r & 63; transpose_item(P.w_ukv, 2048, kb * 64, wukv_src(vg), WUKV, KVLORA, vg * 32, kb * 64, P.g_kv, scr, lane); continue; } r -= I_UKV;
;           { const int kb = r >> 5, nb = r & 31; transpose_item(P.w_out, 1024, kb * 64, nb * 32, WOUT, 1024, nb * 32, kb * 64, nullptr, scr, lane); }
.LBB0_85:
	s_cmpk_gt_i32 s12, 0xf7f
	s_mov_b64 s[2:3], -1
	s_cbranch_scc0 .LBB0_158
	s_cmpk_gt_u32 s12, 0x137f
	s_cbranch_scc0 .LBB0_152
	s_cmpk_gt_u32 s12, 0x149f
	s_cbranch_scc0 .LBB0_121
	s_cmpk_gt_u32 s12, 0x159f
	s_cbranch_scc0 .LBB0_90
	s_and_b32 s0, s16, 0x7fffffc0
	s_add_i32 s2, s0, 0xffffd4c0
	s_and_b32 s8, s14, 0x3e0
	v_or_b32_e32 v0, s2, v44
	s_lshl_b32 s0, s8, 2
	v_or_b32_e32 v28, 2, v0
	v_mov_b32_e32 v29, v1
	v_or_b32_e32 v30, 4, v0
	v_mov_b32_e32 v31, v1
	v_or_b32_e32 v32, 6, v0
	v_mov_b32_e32 v33, v1
	v_or_b32_e32 v34, 8, v0
	v_mov_b32_e32 v35, v1
	v_or_b32_e32 v36, 10, v0
	v_mov_b32_e32 v37, v1
	v_or_b32_e32 v38, 12, v0
	v_mov_b32_e32 v39, v1
	v_lshl_add_u64 v[24:25], v[12:13], 0, s[0:1]
	v_lshlrev_b64 v[26:27], 12, v[0:1]
	v_lshlrev_b64 v[28:29], 12, v[28:29]
	v_lshlrev_b64 v[30:31], 12, v[30:31]
	v_lshlrev_b64 v[32:33], 12, v[32:33]
	v_lshlrev_b64 v[34:35], 12, v[34:35]
	v_lshlrev_b64 v[36:37], 12, v[36:37]
	v_lshlrev_b64 v[38:39], 12, v[38:39]
	v_or_b32_e32 v40, 14, v0
	v_mov_b32_e32 v41, v1
	v_lshl_add_u64 v[26:27], v[24:25], 0, v[26:27]
	v_lshl_add_u64 v[28:29], v[24:25], 0, v[28:29]
	v_lshl_add_u64 v[30:31], v[24:25], 0, v[30:31]
	v_lshl_add_u64 v[32:33], v[24:25], 0, v[32:33]
	v_lshl_add_u64 v[34:35], v[24:25], 0, v[34:35]
	v_lshl_add_u64 v[36:37], v[24:25], 0, v[36:37]
	v_lshl_add_u64 v[38:39], v[24:25], 0, v[38:39]
	v_lshlrev_b64 v[40:41], 12, v[40:41]
	v_lshl_add_u64 v[40:41], v[24:25], 0, v[40:41]
	global_load_dword v42, v[26:27], off nt
	global_load_dword v43, v[28:29], off nt
	global_load_dword v71, v[30:31], off nt
	global_load_dword v72, v[32:33], off nt
	global_load_dword v73, v[34:35], off nt
	global_load_dword v74, v[36:37], off nt
	global_load_dword v75, v[38:39], off nt
	global_load_dword v76, v[40:41], off nt
	v_or_b32_e32 v26, 16, v0
	v_mov_b32_e32 v27, v1
	v_or_b32_e32 v28, 18, v0
	v_mov_b32_e32 v29, v1
	v_or_b32_e32 v30, 20, v0
	v_mov_b32_e32 v31, v1
	v_or_b32_e32 v32, 22, v0
	v_mov_b32_e32 v33, v1
	v_or_b32_e32 v34, 24, v0
	v_mov_b32_e32 v35, v1
	v_or_b32_e32 v36, 26, v0
	v_mov_b32_e32 v37, v1
	v_or_b32_e32 v38, 28, v0
	v_mov_b32_e32 v39, v1
	v_lshlrev_b64 v[26:27], 12, v[26:27]
	v_lshlrev_b64 v[28:29], 12, v[28:29]
	v_lshlrev_b64 v[30:31], 12, v[30:31]
	v_lshlrev_b64 v[32:33], 12, v[32:33]
	v_lshlrev_b64 v[34:35], 12, v[34:35]
	v_lshlrev_b64 v[36:37], 12, v[36:37]
	v_lshlrev_b64 v[38:39], 12, v[38:39]
	v_or_b32_e32 v40, 30, v0
	v_mov_b32_e32 v41, v1
	v_lshl_add_u64 v[26:27], v[24:25], 0, v[26:27]
	v_lshl_add_u64 v[28:29], v[24:25], 0, v[28:29]
	v_lshl_add_u64 v[30:31], v[24:25], 0, v[30:31]
	v_lshl_add_u64 v[32:33], v[24:25], 0, v[32:33]
	v_lshl_add_u64 v[34:35], v[24:25], 0, v[34:35]
	v_lshl_add_u64 v[36:37], v[24:25], 0, v[36:37]
	v_lshl_add_u64 v[38:39], v[24:25], 0, v[38:39]
	v_lshlrev_b64 v[40:41], 12, v[40:41]
	v_lshl_add_u64 v[40:41], v[24:25], 0, v[40:41]
	global_load_dword v77, v[26:27], off nt
	global_load_dword v78, v[28:29], off nt
	global_load_dword v79, v[30:31], off nt
	global_load_dword v80, v[32:33], off nt
	global_load_dword v81, v[34:35], off nt
	global_load_dword v82, v[36:37], off nt
	global_load_dword v83, v[38:39], off nt
	global_load_dword v84, v[40:41], off nt
	v_or_b32_e32 v26, 32, v0
	v_mov_b32_e32 v27, v1
	v_or_b32_e32 v28, 34, v0
	v_mov_b32_e32 v29, v1
	v_or_b32_e32 v30, 36, v0
	v_mov_b32_e32 v31, v1
	v_or_b32_e32 v32, 38, v0
	v_mov_b32_e32 v33, v1
	v_or_b32_e32 v34, 40, v0
	v_mov_b32_e32 v35, v1
	v_or_b32_e32 v36, 42, v0
	v_mov_b32_e32 v37, v1
	v_or_b32_e32 v38, 44, v0
	v_mov_b32_e32 v39, v1
	v_lshlrev_b64 v[26:27], 12, v[26:27]
	v_lshlrev_b64 v[28:29], 12, v[28:29]
	v_lshlrev_b64 v[30:31], 12, v[30:31]
	v_lshlrev_b64 v[32:33], 12, v[32:33]
	v_lshlrev_b64 v[34:35], 12, v[34:35]
	v_lshlrev_b64 v[36:37], 12, v[36:37]
	v_lshlrev_b64 v[38:39], 12, v[38:39]
	v_or_b32_e32 v40, 46, v0
	v_mov_b32_e32 v41, v1
	v_lshl_add_u64 v[26:27], v[24:25], 0, v[26:27]
	v_lshl_add_u64 v[28:29], v[24:25], 0, v[28:29]
	v_lshl_add_u64 v[30:31], v[24:25], 0, v[30:31]
	v_lshl_add_u64 v[32:33], v[24:25], 0, v[32:33]
	v_lshl_add_u64 v[34:35], v[24:25], 0, v[34:35]
	v_lshl_add_u64 v[36:37], v[24:25], 0, v[36:37]
	v_lshl_add_u64 v[38:39], v[24:25], 0, v[38:39]
	v_lshlrev_b64 v[40:41], 12, v[40:41]
	v_lshl_add_u64 v[40:41], v[24:25], 0, v[40:41]
	global_load_dword v85, v[26:27], off nt
	global_load_dword v86, v[28:29], off nt
	global_load_dword v87, v[30:31], off nt
	global_load_dword v88, v[32:33], off nt
	global_load_dword v89, v[34:35], off nt
	global_load_dword v90, v[36:37], off nt
	global_load_dword v91, v[38:39], off nt
	global_load_dword v92, v[40:41], off nt
	v_or_b32_e32 v26, 48, v0
	v_mov_b32_e32 v27, v1
	v_or_b32_e32 v28, 50, v0
	v_mov_b32_e32 v29, v1
	v_or_b32_e32 v30, 52, v0
	v_mov_b32_e32 v31, v1
	v_or_b32_e32 v32, 54, v0
	v_mov_b32_e32 v33, v1
	v_or_b32_e32 v34, 56, v0
	v_mov_b32_e32 v35, v1
	v_or_b32_e32 v36, 58, v0
	v_mov_b32_e32 v37, v1
	v_or_b32_e32 v38, 60, v0
	v_mov_b32_e32 v39, v1
	v_or_b32_e32 v0, 62, v0
	v_lshlrev_b64 v[26:27], 12, v[26:27]
	v_lshlrev_b64 v[28:29], 12, v[28:29]
	v_lshlrev_b64 v[30:31], 12, v[30:31]
	v_lshlrev_b64 v[32:33], 12, v[32:33]
	v_lshlrev_b64 v[34:35], 12, v[34:35]
	v_lshlrev_b64 v[36:37], 12, v[36:37]
	v_lshlrev_b64 v[38:39], 12, v[38:39]
	v_lshlrev_b64 v[40:41], 12, v[0:1]
	v_lshl_add_u64 v[26:27], v[24:25], 0, v[26:27]
	v_lshl_add_u64 v[28:29], v[24:25], 0, v[28:29]
	v_lshl_add_u64 v[30:31], v[24:25], 0, v[30:31]
	v_lshl_add_u64 v[32:33], v[24:25], 0, v[32:33]
	v_lshl_add_u64 v[34:35], v[24:25], 0, v[34:35]
	v_lshl_add_u64 v[36:37], v[24:25], 0, v[36:37]
	v_lshl_add_u64 v[38:39], v[24:25], 0, v[38:39]
	v_lshl_add_u64 v[24:25], v[24:25], 0, v[40:41]
	global_load_dword v0, v[26:27], off nt
	s_nop 0
	global_load_dword v26, v[28:29], off nt
	global_load_dword v27, v[30:31], off nt
	s_nop 0
	global_load_dword v28, v[32:33], off nt
	global_load_dword v29, v[34:35], off nt
	global_load_dword v30, v[36:37], off nt
	global_load_dword v31, v[38:39], off nt
	s_nop 0
	global_load_dword v24, v[24:25], off nt
	s_waitcnt vmcnt(30)
; #define LAS __attribute__((address_space(3)))
; __device__ __forceinline__ unsigned pk2(float lo, float hi) { f32x2_t v = {lo, hi}; bf16x2_t b = __builtin_convertvector(v, bf16x2_t); return __builtin_bit_cast(unsigned, b); }
; __device__ __forceinline__ void transpose_item(const float* W, int ldw, int k0, int srcn0, bf16_t* WT, int ldk, int dstrow0, int dstk0, const float* ksc, LAS float* scr, int lane) {
;     ...
;     for (int i = 0; i < 32; ++i) { const int kk = 2 * i + (lane >> 5); float v = tv[i]; if (srcn0 >= 0 && ksc) v *= ksc[k0 + kk];
;         scr[kk * 33 + (lane & 31)] = v; }
;     asm volatile("s_waitcnt lgkmcnt(0)" ::: "memory");
;     const int c = lane & 7;
; #pragma unroll
;     for (int j = 0; j < 4; ++j) { const int n = (lane >> 3) + 8 * j; const LAS float* s = scr + (8 * c) * 33 + n;
;         u32x4 o; o.x = pk2(s[0 * 33], s[1 * 33]); o.y = pk2(s[2 * 33], s[3 * 33]); o.z = pk2(s[4 * 33], s[5 * 33]); o.w = pk2(s[6 * 33], s[7 * 33]);
;         *(u32x4*)(WT + (size_t)(dstrow0 + n) * ldk + dstk0 + 8 * c) = o; }
;     asm volatile("s_waitcnt lgkmcnt(0)" ::: "memory");
	ds_write2_b32 v46, v42, v43 offset1:66
	s_waitcnt vmcnt(28)
	ds_write2_b32 v46, v71, v72 offset0:132 offset1:198
	s_waitcnt vmcnt(26)
	ds_write2_b32 v64, v73, v74 offset0:8 offset1:74
	s_waitcnt vmcnt(24)
	ds_write2_b32 v64, v75, v76 offset0:140 offset1:206
	s_waitcnt vmcnt(22)
	ds_write2_b32 v65, v77, v78 offset0:16 offset1:82
	s_waitcnt vmcnt(20)
	ds_write2_b32 v65, v79, v80 offset0:148 offset1:214
	s_waitcnt vmcnt(18)
	ds_write2_b32 v66, v81, v82 offset0:24 offset1:90
	s_waitcnt vmcnt(16)
	ds_write2_b32 v66, v83, v84 offset0:156 offset1:222
	s_waitcnt vmcnt(14)
	ds_write2_b32 v67, v85, v86 offset0:32 offset1:98
	s_waitcnt vmcnt(12)
	ds_write2_b32 v67, v87, v88 offset0:164 offset1:230
	s_waitcnt vmcnt(10)
	ds_write2_b32 v68, v89, v90 offset0:40 offset1:106
	s_waitcnt vmcnt(8)
	ds_write2_b32 v68, v91, v92 offset0:172 offset1:238
	s_waitcnt vmcnt(6)
	ds_write2_b32 v69, v0, v26 offset0:48 offset1:114
	s_waitcnt vmcnt(4)
	ds_write2_b32 v69, v27, v28 offset0:180 offset1:246
	s_waitcnt vmcnt(2)
	ds_write2_b32 v70, v29, v30 offset0:56 offset1:122
	s_waitcnt vmcnt(0)
	ds_write2_b32 v70, v31, v24 offset0:188 offset1:254
	s_waitcnt lgkmcnt(0)
	ds_read2_b32 v[28:29], v48 offset0:33 offset1:41
	ds_read2_b32 v[30:31], v48 offset1:8
	ds_read2_b32 v[32:33], v48 offset0:66 offset1:74
	ds_read2_b32 v[34:35], v48 offset0:99 offset1:107
	ds_read2_b32 v[36:37], v48 offset0:132 offset1:140
	ds_read2_b32 v[38:39], v48 offset0:165 offset1:173
	ds_read2_b32 v[40:41], v48 offset0:198 offset1:206
	ds_read2_b32 v[42:43], v48 offset0:231 offset1:239
	s_mov_b32 s3, s1
	v_or_b32_e32 v0, s8, v47
	v_lshl_add_u64 v[72:73], s[2:3], 1, v[2:3]
	v_lshlrev_b32_e32 v0, 11, v0
	s_waitcnt lgkmcnt(6)
	v_cvt_pk_bf16_f32 v24, v30, v28
	s_waitcnt lgkmcnt(4)
	v_cvt_pk_bf16_f32 v25, v32, v34
	s_waitcnt lgkmcnt(2)
	v_cvt_pk_bf16_f32 v26, v36, v38
	s_waitcnt lgkmcnt(0)
	v_cvt_pk_bf16_f32 v27, v40, v42
	v_lshl_add_u64 v[74:75], v[72:73], 0, v[0:1]
	global_store_dwordx4 v[74:75], v[24:27], off sc0 sc1
	v_or_b32_e32 v0, s8, v49
	v_lshlrev_b32_e32 v0, 11, v0
	v_cvt_pk_bf16_f32 v24, v31, v29
	v_cvt_pk_bf16_f32 v25, v33, v35
	v_cvt_pk_bf16_f32 v26, v37, v39
	v_cvt_pk_bf16_f32 v27, v41, v43
	ds_read2_b32 v[30:31], v48 offset0:49 offset1:57
	ds_read2_b32 v[32:33], v48 offset0:16 offset1:24
	ds_read2_b32 v[34:35], v48 offset0:82 offset1:90
	ds_read2_b32 v[36:37], v48 offset0:115 offset1:123
	ds_read2_b32 v[38:39], v48 offset0:148 offset1:156
	ds_read2_b32 v[40:41], v48 offset0:181 offset1:189
	ds_read2_b32 v[42:43], v48 offset0:214 offset1:222
	ds_read2_b32 v[74:75], v48 offset0:247 offset1:255
	v_lshl_add_u64 v[28:29], v[72:73], 0, v[0:1]
	v_or_b32_e32 v0, s8, v50
	v_lshlrev_b32_e32 v0, 11, v0
	global_store_dwordx4 v[28:29], v[24:27], off sc0 sc1
	v_lshl_add_u64 v[28:29], v[72:73], 0, v[0:1]
	v_or_b32_e32 v0, s8, v51
	s_waitcnt lgkmcnt(6)
	v_cvt_pk_bf16_f32 v24, v32, v30
	s_waitcnt lgkmcnt(4)
	v_cvt_pk_bf16_f32 v25, v34, v36
	s_waitcnt lgkmcnt(2)
	v_cvt_pk_bf16_f32 v26, v38, v40
	s_waitcnt lgkmcnt(0)
	v_cvt_pk_bf16_f32 v27, v42, v74
	v_lshlrev_b32_e32 v0, 11, v0
	global_store_dwordx4 v[28:29], v[24:27], off sc0 sc1
	v_lshl_add_u64 v[28:29], v[72:73], 0, v[0:1]
	s_mov_b64 s[2:3], 0
	v_cvt_pk_bf16_f32 v24, v33, v31
	v_cvt_pk_bf16_f32 v25, v35, v37
	v_cvt_pk_bf16_f32 v26, v39, v41
	v_cvt_pk_bf16_f32 v27, v43, v75
	global_store_dwordx4 v[28:29], v[24:27], off sc0 sc1
	s_waitcnt lgkmcnt(0)

; #define LAS __attribute__((address_space(3)))
; __device__ __forceinline__ unsigned pk2(float lo, float hi) { f32x2_t v = {lo, hi}; bf16x2_t b = __builtin_convertvector(v, bf16x2_t); return __builtin_bit_cast(unsigned, b); }
; __device__ __forceinline__ void transpose_item(const float* W, int ldw, int k0, int srcn0, bf16_t* WT, int ldk, int dstrow0, int dstk0, const float* ksc, LAS float* scr, int lane) {
;     ...
;     for (int i = 0; i < 32; ++i) { const int kk = 2 * i + (lane >> 5); float v = tv[i]; if (srcn0 >= 0 && ksc) v *= ksc[k0 + kk];
;         scr[kk * 33 + (lane & 31)] = v; }
;     asm volatile("s_waitcnt lgkmcnt(0)" ::: "memory");
;     const int c = lane & 7;
; #pragma unroll
;     for (int j = 0; j < 4; ++j) { const int n = (lane >> 3) + 8 * j; const LAS float* s = scr + (8 * c) * 33 + n;
;         u32x4 o; o.x = pk2(s[0 * 33], s[1 * 33]); o.y = pk2(s[2 * 33], s[3 * 33]); o.z = pk2(s[4 * 33], s[5 * 33]); o.w = pk2(s[6 * 33], s[7 * 33]);
;         *(u32x4*)(WT + (size_t)(dstrow0 + n) * ldk + dstk0 + 8 * c) = o; }
;     asm volatile("s_waitcnt lgkmcnt(0)" ::: "memory");
.LBB0_119:
	ds_write2_b32 v0, v26, v27 offset0:148 offset1:214
	s_waitcnt lgkmcnt(0)
	s_waitcnt vmcnt(4)
	ds_read2_b32 v[28:29], v48 offset0:33 offset1:41
	ds_read2_b32 v[30:31], v48 offset1:8
	ds_read2_b32 v[32:33], v48 offset0:66 offset1:74
	ds_read2_b32 v[34:35], v48 offset0:99 offset1:107
	ds_read2_b32 v[36:37], v48 offset0:132 offset1:140
	ds_read2_b32 v[38:39], v48 offset0:165 offset1:173
	ds_read2_b32 v[40:41], v48 offset0:198 offset1:206
	ds_read2_b32 v[42:43], v48 offset0:231 offset1:239
	v_or_b32_e32 v0, s10, v47
	s_waitcnt vmcnt(2)
	v_lshl_add_u64 v[72:73], s[0:1], 1, v[4:5]
	v_lshlrev_b32_e32 v0, 9, v0
	s_waitcnt vmcnt(1) lgkmcnt(6)
	v_cvt_pk_bf16_f32 v24, v30, v28
	s_waitcnt vmcnt(0) lgkmcnt(4)
	v_cvt_pk_bf16_f32 v25, v32, v34
	s_waitcnt lgkmcnt(2)
	v_cvt_pk_bf16_f32 v26, v36, v38
	s_waitcnt lgkmcnt(0)
	v_cvt_pk_bf16_f32 v27, v40, v42
	v_lshl_add_u64 v[74:75], v[72:73], 0, v[0:1]
	global_store_dwordx4 v[74:75], v[24:27], off sc0 sc1
	v_or_b32_e32 v0, s10, v49
	v_lshlrev_b32_e32 v0, 9, v0
	v_cvt_pk_bf16_f32 v24, v31, v29
	v_cvt_pk_bf16_f32 v25, v33, v35
	v_cvt_pk_bf16_f32 v26, v37, v39
	v_cvt_pk_bf16_f32 v27, v41, v43
	ds_read2_b32 v[30:31], v48 offset0:49 offset1:57
	ds_read2_b32 v[32:33], v48 offset0:16 offset1:24
	ds_read2_b32 v[34:35], v48 offset0:82 offset1:90
	ds_read2_b32 v[36:37], v48 offset0:115 offset1:123
	ds_read2_b32 v[38:39], v48 offset0:148 offset1:156
	ds_read2_b32 v[40:41], v48 offset0:181 offset1:189
	ds_read2_b32 v[42:43], v48 offset0:214 offset1:222
	ds_read2_b32 v[74:75], v48 offset0:247 offset1:255
	v_lshl_add_u64 v[28:29], v[72:73], 0, v[0:1]
	v_or_b32_e32 v0, s10, v50
	v_lshlrev_b32_e32 v0, 9, v0
	global_store_dwordx4 v[28:29], v[24:27], off sc0 sc1
	v_lshl_add_u64 v[28:29], v[72:73], 0, v[0:1]
	v_or_b32_e32 v0, s10, v51
	s_waitcnt lgkmcnt(6)
	v_cvt_pk_bf16_f32 v24, v32, v30
	s_waitcnt lgkmcnt(4)
	v_cvt_pk_bf16_f32 v25, v34, v36
	s_waitcnt lgkmcnt(2)
	v_cvt_pk_bf16_f32 v26, v38, v40
	s_waitcnt lgkmcnt(0)
	v_cvt_pk_bf16_f32 v27, v42, v74
	v_lshlrev_b32_e32 v0, 9, v0
	global_store_dwordx4 v[28:29], v[24:27], off sc0 sc1
	v_lshl_add_u64 v[28:29], v[72:73], 0, v[0:1]
	s_nop 0
	v_cvt_pk_bf16_f32 v24, v33, v31
	v_cvt_pk_bf16_f32 v25, v35, v37
	v_cvt_pk_bf16_f32 v26, v39, v41
	v_cvt_pk_bf16_f32 v27, v43, v75
	global_store_dwordx4 v[28:29], v[24:27], off sc0 sc1
	s_waitcnt lgkmcnt(0)

; #define LAS __attribute__((address_space(3)))
; __device__ __forceinline__ unsigned pk2(float lo, float hi) { f32x2_t v = {lo, hi}; bf16x2_t b = __builtin_convertvector(v, bf16x2_t); return __builtin_bit_cast(unsigned, b); }
; __device__ __forceinline__ void transpose_item(const float* W, int ldw, int k0, int srcn0, bf16_t* WT, int ldk, int dstrow0, int dstk0, const float* ksc, LAS float* scr, int lane) {
;     ...
;     for (int i = 0; i < 32; ++i) { const int kk = 2 * i + (lane >> 5); float v = tv[i]; if (srcn0 >= 0 && ksc) v *= ksc[k0 + kk];
;         scr[kk * 33 + (lane & 31)] = v; }
;     asm volatile("s_waitcnt lgkmcnt(0)" ::: "memory");
;     const int c = lane & 7;
; #pragma unroll
;     for (int j = 0; j < 4; ++j) { const int n = (lane >> 3) + 8 * j; const LAS float* s = scr + (8 * c) * 33 + n;
;         u32x4 o; o.x = pk2(s[0 * 33], s[1 * 33]); o.y = pk2(s[2 * 33], s[3 * 33]); o.z = pk2(s[4 * 33], s[5 * 33]); o.w = pk2(s[6 * 33], s[7 * 33]);
;         *(u32x4*)(WT + (size_t)(dstrow0 + n) * ldk + dstk0 + 8 * c) = o; }
;     asm volatile("s_waitcnt lgkmcnt(0)" ::: "memory");
.LBB0_150:
	s_waitcnt vmcnt(4)
	ds_write2_b32 v28, v26, v27 offset0:148 offset1:214
	s_waitcnt lgkmcnt(0)
	ds_read2_b32 v[28:29], v48 offset0:33 offset1:41
	ds_read2_b32 v[30:31], v48 offset1:8
	ds_read2_b32 v[32:33], v48 offset0:66 offset1:74
	ds_read2_b32 v[34:35], v48 offset0:99 offset1:107
	ds_read2_b32 v[36:37], v48 offset0:132 offset1:140
	ds_read2_b32 v[38:39], v48 offset0:165 offset1:173
	ds_read2_b32 v[40:41], v48 offset0:198 offset1:206
	s_waitcnt vmcnt(2)
	ds_read2_b32 v[42:43], v48 offset0:231 offset1:239
	s_lshl_b32 s0, s11, 1
	v_or_b32_e32 v0, s10, v47
	v_lshl_add_u64 v[72:73], v[6:7], 0, s[0:1]
	v_mul_i32_i24_e32 v0, 0x180, v0
	s_waitcnt vmcnt(1) lgkmcnt(6)
	v_cvt_pk_bf16_f32 v24, v30, v28
	s_waitcnt vmcnt(0) lgkmcnt(4)
	v_cvt_pk_bf16_f32 v25, v32, v34
	s_waitcnt lgkmcnt(2)
	v_cvt_pk_bf16_f32 v26, v36, v38
	s_waitcnt lgkmcnt(0)
	v_cvt_pk_bf16_f32 v27, v40, v42
	v_lshl_add_u64 v[74:75], v[0:1], 1, v[72:73]
	global_store_dwordx4 v[74:75], v[24:27], off sc0 sc1
	v_or_b32_e32 v0, s10, v49
	v_mul_i32_i24_e32 v0, 0x180, v0
	v_cvt_pk_bf16_f32 v24, v31, v29
	v_cvt_pk_bf16_f32 v25, v33, v35
	v_cvt_pk_bf16_f32 v26, v37, v39
	v_cvt_pk_bf16_f32 v27, v41, v43
	ds_read2_b32 v[30:31], v48 offset0:16 offset1:24
	ds_read2_b32 v[32:33], v48 offset0:49 offset1:57
	ds_read2_b32 v[34:35], v48 offset0:82 offset1:90
	ds_read2_b32 v[36:37], v48 offset0:115 offset1:123
	ds_read2_b32 v[38:39], v48 offset0:148 offset1:156
	ds_read2_b32 v[40:41], v48 offset0:181 offset1:189
	ds_read2_b32 v[42:43], v48 offset0:214 offset1:222
	ds_read2_b32 v[74:75], v48 offset0:247 offset1:255
	v_lshl_add_u64 v[28:29], v[0:1], 1, v[72:73]
	v_or_b32_e32 v0, s10, v50
	v_mul_i32_i24_e32 v0, 0x180, v0
	global_store_dwordx4 v[28:29], v[24:27], off sc0 sc1
	v_lshl_add_u64 v[28:29], v[0:1], 1, v[72:73]
	v_or_b32_e32 v0, s10, v51
	s_waitcnt lgkmcnt(6)
	v_cvt_pk_bf16_f32 v24, v30, v32
	s_waitcnt lgkmcnt(4)
	v_cvt_pk_bf16_f32 v25, v34, v36
	s_waitcnt lgkmcnt(2)
	v_cvt_pk_bf16_f32 v26, v38, v40
	s_waitcnt lgkmcnt(0)
	v_cvt_pk_bf16_f32 v27, v42, v74
	v_mul_i32_i24_e32 v0, 0x180, v0
	global_store_dwordx4 v[28:29], v[24:27], off sc0 sc1
	v_lshl_add_u64 v[28:29], v[0:1], 1, v[72:73]
	s_nop 0
	v_cvt_pk_bf16_f32 v24, v31, v33
	v_cvt_pk_bf16_f32 v25, v35, v37
	v_cvt_pk_bf16_f32 v26, v39, v41
	v_cvt_pk_bf16_f32 v27, v43, v75
	global_store_dwordx4 v[28:29], v[24:27], off sc0 sc1
	s_waitcnt lgkmcnt(0)

; __device__ __forceinline__ void transpose_item(const float* W, int ldw, int k0, int srcn0, bf16_t* WT, int ldk, int dstrow0, int dstk0, const float* ksc, LAS float* scr, int lane) {
;     float tv[32];
; #pragma unroll
;     for (int i = 0; i < 32; ++i) { const int kk = 2 * i + (lane >> 5); tv[i] = 0.f;
;         if (srcn0 >= 0) { tv[i] = __builtin_nontemporal_load(W + (size_t)(k0 + kk) * ldw + srcn0 + (lane & 31)); } }
; __device__ __forceinline__ void phase0(const Ptrs& P, LAS unsigned char* lds, int G) {
;     ...
;           if (r < I_M) { const int kb = r >> 5, nb = r & 31; if (kb < 16) transpose_item(P.w_conv_out, 1024, kb * 64, nb * 32, WM, 2048, nb * 32, kb * 64, nullptr, scr, lane);
;                          else transpose_item(P.w_mla_out, 1024, (kb - 16) * 64, nb * 32, WM, 2048, nb * 32, kb * 64, nullptr, scr, lane); continue; } r -= I_M;
.LBB0_152:
	s_andn2_b64 vcc, exec, s[2:3]
	s_cbranch_vccnz .LBB0_157
	s_add_i32 s2, s16, 0xffffe100
	s_add_i32 s0, s12, 0xfffff080
	s_and_b32 s8, s2, 0x7fffffc0
	s_and_b32 s9, s14, 0x3e0
	s_cmpk_gt_u32 s0, 0x1ff
	s_mov_b64 s[2:3], -1
	v_or_b32_e32 v27, s9, v47
	v_or_b32_e32 v26, s9, v49
	v_or_b32_e32 v25, s9, v50
	v_or_b32_e32 v24, s9, v51
	s_cbranch_scc0 .LBB0_155
	v_add_u32_e32 v28, s8, v63
	v_or_b32_e32 v34, 2, v28
	v_or_b32_e32 v36, 4, v28
	v_or_b32_e32 v38, 6, v28
	v_or_b32_e32 v40, 8, v28
	v_or_b32_e32 v42, 10, v28
	v_or_b32_e32 v72, 12, v28
	v_or_b32_e32 v74, 14, v28
	s_lshl_b32 s0, s9, 2
	v_ashrrev_i32_e32 v29, 31, v28
	v_ashrrev_i32_e32 v35, 31, v34
	v_ashrrev_i32_e32 v37, 31, v36
	v_ashrrev_i32_e32 v39, 31, v38
	v_ashrrev_i32_e32 v41, 31, v40
	v_ashrrev_i32_e32 v43, 31, v42
	v_ashrrev_i32_e32 v73, 31, v72
	v_ashrrev_i32_e32 v75, 31, v74
	v_lshl_add_u64 v[30:31], v[18:19], 0, s[0:1]
	v_lshlrev_b64 v[32:33], 12, v[28:29]
	v_lshlrev_b64 v[34:35], 12, v[34:35]
	v_lshlrev_b64 v[36:37], 12, v[36:37]
	v_lshlrev_b64 v[38:39], 12, v[38:39]
	v_lshlrev_b64 v[40:41], 12, v[40:41]
	v_lshlrev_b64 v[42:43], 12, v[42:43]
	v_lshlrev_b64 v[72:73], 12, v[72:73]
	v_lshlrev_b64 v[74:75], 12, v[74:75]
	v_lshl_add_u64 v[32:33], v[30:31], 0, v[32:33]
	v_lshl_add_u64 v[34:35], v[30:31], 0, v[34:35]
	v_lshl_add_u64 v[36:37], v[30:31], 0, v[36:37]
	v_lshl_add_u64 v[38:39], v[30:31], 0, v[38:39]
	v_lshl_add_u64 v[40:41], v[30:31], 0, v[40:41]
	v_lshl_add_u64 v[42:43], v[30:31], 0, v[42:43]
	v_lshl_add_u64 v[72:73], v[30:31], 0, v[72:73]
	v_lshl_add_u64 v[74:75], v[30:31], 0, v[74:75]
	global_load_dword v0, v[32:33], off nt
	global_load_dword v71, v[34:35], off nt
	global_load_dword v76, v[36:37], off nt
	global_load_dword v77, v[38:39], off nt
	global_load_dword v78, v[40:41], off nt
	global_load_dword v79, v[42:43], off nt
	global_load_dword v80, v[72:73], off nt
	global_load_dword v81, v[74:75], off nt
	v_or_b32_e32 v32, 16, v28
	v_or_b32_e32 v34, 18, v28
	v_or_b32_e32 v36, 20, v28
	v_or_b32_e32 v38, 22, v28
	v_or_b32_e32 v40, 24, v28
	v_or_b32_e32 v42, 26, v28
	v_or_b32_e32 v72, 28, v28
	v_or_b32_e32 v74, 30, v28
	v_ashrrev_i32_e32 v33, 31, v32
	v_ashrrev_i32_e32 v35, 31, v34
	v_ashrrev_i32_e32 v37, 31, v36
	v_ashrrev_i32_e32 v39, 31, v38
	v_ashrrev_i32_e32 v41, 31, v40
	v_ashrrev_i32_e32 v43, 31, v42
	v_ashrrev_i32_e32 v73, 31, v72
	v_ashrrev_i32_e32 v75, 31, v74
	v_lshlrev_b64 v[32:33], 12, v[32:33]
	v_lshlrev_b64 v[34:35], 12, v[34:35]
	v_lshlrev_b64 v[36:37], 12, v[36:37]
	v_lshlrev_b64 v[38:39], 12, v[38:39]
	v_lshlrev_b64 v[40:41], 12, v[40:41]
	v_lshlrev_b64 v[42:43], 12, v[42:43]
	v_lshlrev_b64 v[72:73], 12, v[72:73]
	v_lshlrev_b64 v[74:75], 12, v[74:75]
	v_lshl_add_u64 v[32:33], v[30:31], 0, v[32:33]
	v_lshl_add_u64 v[34:35], v[30:31], 0, v[34:35]
	v_lshl_add_u64 v[36:37], v[30:31], 0, v[36:37]
	v_lshl_add_u64 v[38:39], v[30:31], 0, v[38:39]
	v_lshl_add_u64 v[40:41], v[30:31], 0, v[40:41]
	v_lshl_add_u64 v[42:43], v[30:31], 0, v[42:43]
	v_lshl_add_u64 v[72:73], v[30:31], 0, v[72:73]
	v_lshl_add_u64 v[74:75], v[30:31], 0, v[74:75]
	global_load_dword v82, v[32:33], off nt
	global_load_dword v83, v[34:35], off nt
	global_load_dword v84, v[36:37], off nt
	global_load_dword v85, v[38:39], off nt
	global_load_dword v86, v[40:41], off nt
	global_load_dword v87, v[42:43], off nt
	global_load_dword v88, v[72:73], off nt
	global_load_dword v89, v[74:75], off nt
	v_or_b32_e32 v32, 32, v28
	v_or_b32_e32 v34, 34, v28
	v_or_b32_e32 v36, 36, v28
	v_or_b32_e32 v38, 38, v28
	v_or_b32_e32 v40, 40, v28
	v_or_b32_e32 v42, 42, v28
	v_or_b32_e32 v72, 44, v28
	v_or_b32_e32 v74, 46, v28
	v_ashrrev_i32_e32 v33, 31, v32
	v_ashrrev_i32_e32 v35, 31, v34
	v_ashrrev_i32_e32 v37, 31, v36
	v_ashrrev_i32_e32 v39, 31, v38
	v_ashrrev_i32_e32 v41, 31, v40
	v_ashrrev_i32_e32 v43, 31, v42
	v_ashrrev_i32_e32 v73, 31, v72
	v_ashrrev_i32_e32 v75, 31, v74
	v_lshlrev_b64 v[32:33], 12, v[32:33]
	v_lshlrev_b64 v[34:35], 12, v[34:35]
	v_lshlrev_b64 v[36:37], 12, v[36:37]
	v_lshlrev_b64 v[38:39], 12, v[38:39]
	v_lshlrev_b64 v[40:41], 12, v[40:41]
	v_lshlrev_b64 v[42:43], 12, v[42:43]
	v_lshlrev_b64 v[72:73], 12, v[72:73]
	v_lshlrev_b64 v[74:75], 12, v[74:75]
	v_lshl_add_u64 v[32:33], v[30:31], 0, v[32:33]
	v_lshl_add_u64 v[34:35], v[30:31], 0, v[34:35]
	v_lshl_add_u64 v[36:37], v[30:31], 0, v[36:37]
	v_lshl_add_u64 v[38:39], v[30:31], 0, v[38:39]
	v_lshl_add_u64 v[40:41], v[30:31], 0, v[40:41]
	v_lshl_add_u64 v[42:43], v[30:31], 0, v[42:43]
	v_lshl_add_u64 v[72:73], v[30:31], 0, v[72:73]
	v_lshl_add_u64 v[74:75], v[30:31], 0, v[74:75]
	global_load_dword v90, v[32:33], off nt
	global_load_dword v91, v[34:35], off nt
	global_load_dword v92, v[36:37], off nt
	global_load_dword v93, v[38:39], off nt
	global_load_dword v94, v[40:41], off nt
	global_load_dword v95, v[42:43], off nt
	global_load_dword v96, v[72:73], off nt
	s_nop 0
	global_load_dword v74, v[74:75], off nt
	v_or_b32_e32 v32, 48, v28
	v_or_b32_e32 v34, 50, v28
	v_or_b32_e32 v36, 52, v28
	v_or_b32_e32 v38, 54, v28
	v_or_b32_e32 v40, 56, v28
	v_or_b32_e32 v42, 58, v28
	v_or_b32_e32 v72, 60, v28
	v_or_b32_e32 v28, 62, v28
	v_ashrrev_i32_e32 v33, 31, v32
	v_ashrrev_i32_e32 v35, 31, v34
	v_ashrrev_i32_e32 v37, 31, v36
	v_ashrrev_i32_e32 v29, 31, v28
	v_lshlrev_b64 v[32:33], 12, v[32:33]
	v_lshlrev_b64 v[34:35], 12, v[34:35]
	v_lshlrev_b64 v[36:37], 12, v[36:37]
	v_ashrrev_i32_e32 v39, 31, v38
	v_ashrrev_i32_e32 v41, 31, v40
	v_ashrrev_i32_e32 v43, 31, v42
	v_ashrrev_i32_e32 v73, 31, v72
	v_lshlrev_b64 v[28:29], 12, v[28:29]
	v_lshl_add_u64 v[32:33], v[30:31], 0, v[32:33]
	v_lshl_add_u64 v[34:35], v[30:31], 0, v[34:35]
	v_lshl_add_u64 v[36:37], v[30:31], 0, v[36:37]
	v_lshlrev_b64 v[38:39], 12, v[38:39]
	v_lshlrev_b64 v[40:41], 12, v[40:41]
	v_lshlrev_b64 v[42:43], 12, v[42:43]
	v_lshlrev_b64 v[72:73], 12, v[72:73]
	v_lshl_add_u64 v[28:29], v[30:31], 0, v[28:29]
	v_lshl_add_u64 v[38:39], v[30:31], 0, v[38:39]
	v_lshl_add_u64 v[40:41], v[30:31], 0, v[40:41]
	v_lshl_add_u64 v[42:43], v[30:31], 0, v[42:43]
	v_lshl_add_u64 v[72:73], v[30:31], 0, v[72:73]
	global_load_dword v30, v[32:33], off nt
	global_load_dword v31, v[34:35], off nt
	s_nop 0
	global_load_dword v32, v[36:37], off nt
	global_load_dword v33, v[38:39], off nt
	global_load_dword v34, v[40:41], off nt
	global_load_dword v35, v[42:43], off nt
	s_nop 0
	global_load_dword v36, v[72:73], off nt
	s_nop 0
	global_load_dword v28, v[28:29], off nt
	s_waitcnt vmcnt(30)
; #define LAS __attribute__((address_space(3)))
; __device__ __forceinline__ unsigned pk2(float lo, float hi) { f32x2_t v = {lo, hi}; bf16x2_t b = __builtin_convertvector(v, bf16x2_t); return __builtin_bit_cast(unsigned, b); }
; __device__ __forceinline__ void transpose_item(const float* W, int ldw, int k0, int srcn0, bf16_t* WT, int ldk, int dstrow0, int dstk0, const float* ksc, LAS float* scr, int lane) {
;     ...
;     for (int i = 0; i < 32; ++i) { const int kk = 2 * i + (lane >> 5); float v = tv[i]; if (srcn0 >= 0 && ksc) v *= ksc[k0 + kk];
;         scr[kk * 33 + (lane & 31)] = v; }
;     asm volatile("s_waitcnt lgkmcnt(0)" ::: "memory");
;     const int c = lane & 7;
; #pragma unroll
;     for (int j = 0; j < 4; ++j) { const int n = (lane >> 3) + 8 * j; const LAS float* s = scr + (8 * c) * 33 + n;
;         u32x4 o; o.x = pk2(s[0 * 33], s[1 * 33]); o.y = pk2(s[2 * 33], s[3 * 33]); o.z = pk2(s[4 * 33], s[5 * 33]); o.w = pk2(s[6 * 33], s[7 * 33]);
;         *(u32x4*)(WT + (size_t)(dstrow0 + n) * ldk + dstk0 + 8 * c) = o; }
;     asm volatile("s_waitcnt lgkmcnt(0)" ::: "memory");
; __device__ __forceinline__ void phase0(const Ptrs& P, LAS unsigned char* lds, int G) {
;     ...
;           if (r < I_M) { const int kb = r >> 5, nb = r & 31; if (kb < 16) transpose_item(P.w_conv_out, 1024, kb * 64, nb * 32, WM, 2048, nb * 32, kb * 64, nullptr, scr, lane);
;                          else transpose_item(P.w_mla_out, 1024, (kb - 16) * 64, nb * 32, WM, 2048, nb * 32, kb * 64, nullptr, scr, lane); continue; } r -= I_M;
	ds_write2_b32 v46, v0, v71 offset1:66
	s_waitcnt vmcnt(28)
	ds_write2_b32 v46, v76, v77 offset0:132 offset1:198
	s_waitcnt vmcnt(26)
	ds_write2_b32 v64, v78, v79 offset0:8 offset1:74
	s_waitcnt vmcnt(24)
	ds_write2_b32 v64, v80, v81 offset0:140 offset1:206
	s_waitcnt vmcnt(22)
	ds_write2_b32 v65, v82, v83 offset0:16 offset1:82
	s_waitcnt vmcnt(20)
	ds_write2_b32 v65, v84, v85 offset0:148 offset1:214
	s_waitcnt vmcnt(18)
	ds_write2_b32 v66, v86, v87 offset0:24 offset1:90
	s_waitcnt vmcnt(16)
	ds_write2_b32 v66, v88, v89 offset0:156 offset1:222
	s_waitcnt vmcnt(14)
	ds_write2_b32 v67, v90, v91 offset0:32 offset1:98
	s_waitcnt vmcnt(12)
	ds_write2_b32 v67, v92, v93 offset0:164 offset1:230
	s_waitcnt vmcnt(10)
	ds_write2_b32 v68, v94, v95 offset0:40 offset1:106
	s_waitcnt vmcnt(8)
	ds_write2_b32 v68, v96, v74 offset0:172 offset1:238
	s_waitcnt vmcnt(6)
	ds_write2_b32 v69, v30, v31 offset0:48 offset1:114
	s_waitcnt vmcnt(4)
	ds_write2_b32 v69, v32, v33 offset0:180 offset1:246
	s_waitcnt vmcnt(2)
	ds_write2_b32 v70, v34, v35 offset0:56 offset1:122
	s_waitcnt vmcnt(0)
	ds_write2_b32 v70, v36, v28 offset0:188 offset1:254
	s_waitcnt lgkmcnt(0)
	ds_read2_b32 v[32:33], v48 offset0:33 offset1:41
	ds_read2_b32 v[34:35], v48 offset1:8
	ds_read2_b32 v[36:37], v48 offset0:66 offset1:74
	ds_read2_b32 v[38:39], v48 offset0:99 offset1:107
	ds_read2_b32 v[40:41], v48 offset0:132 offset1:140
	ds_read2_b32 v[42:43], v48 offset0:165 offset1:173
	ds_read2_b32 v[72:73], v48 offset0:198 offset1:206
	ds_read2_b32 v[74:75], v48 offset0:231 offset1:239
	s_lshl_b32 s0, s8, 1
	v_lshl_add_u64 v[76:77], v[8:9], 0, s[0:1]
	v_lshlrev_b32_e32 v0, 12, v27
	s_waitcnt lgkmcnt(6)
	v_cvt_pk_bf16_f32 v28, v34, v32
	s_waitcnt lgkmcnt(4)
	v_cvt_pk_bf16_f32 v29, v36, v38
	s_waitcnt lgkmcnt(2)
	v_cvt_pk_bf16_f32 v30, v40, v42
	s_waitcnt lgkmcnt(0)
	v_cvt_pk_bf16_f32 v31, v72, v74
	v_lshl_add_u64 v[78:79], v[76:77], 0, v[0:1]
	global_store_dwordx4 v[78:79], v[28:31], off sc0 sc1
	v_lshlrev_b32_e32 v0, 12, v26
	s_mov_b64 s[2:3], 0
	v_cvt_pk_bf16_f32 v28, v35, v33
	v_cvt_pk_bf16_f32 v29, v37, v39
	v_cvt_pk_bf16_f32 v30, v41, v43
	v_cvt_pk_bf16_f32 v31, v73, v75
	ds_read2_b32 v[34:35], v48 offset0:49 offset1:57
	ds_read2_b32 v[36:37], v48 offset0:16 offset1:24
	ds_read2_b32 v[38:39], v48 offset0:82 offset1:90
	ds_read2_b32 v[40:41], v48 offset0:115 offset1:123
	ds_read2_b32 v[42:43], v48 offset0:148 offset1:156
	ds_read2_b32 v[72:73], v48 offset0:181 offset1:189
	ds_read2_b32 v[74:75], v48 offset0:214 offset1:222
	ds_read2_b32 v[78:79], v48 offset0:247 offset1:255
	v_lshl_add_u64 v[32:33], v[76:77], 0, v[0:1]
	v_lshlrev_b32_e32 v0, 12, v25
	global_store_dwordx4 v[32:33], v[28:31], off sc0 sc1
	v_lshl_add_u64 v[32:33], v[76:77], 0, v[0:1]
	v_lshlrev_b32_e32 v0, 12, v24
	s_waitcnt lgkmcnt(6)
	v_cvt_pk_bf16_f32 v28, v36, v34
	s_waitcnt lgkmcnt(4)
	v_cvt_pk_bf16_f32 v29, v38, v40
	s_waitcnt lgkmcnt(2)
	v_cvt_pk_bf16_f32 v30, v42, v72
	s_waitcnt lgkmcnt(0)
	v_cvt_pk_bf16_f32 v31, v74, v78
	global_store_dwordx4 v[32:33], v[28:31], off sc0 sc1
	v_lshl_add_u64 v[32:33], v[76:77], 0, v[0:1]
	s_nop 0
	v_cvt_pk_bf16_f32 v28, v37, v35
	v_cvt_pk_bf16_f32 v29, v39, v41
	v_cvt_pk_bf16_f32 v30, v43, v73
	v_cvt_pk_bf16_f32 v31, v75, v79
	global_store_dwordx4 v[32:33], v[28:31], off sc0 sc1
	s_waitcnt lgkmcnt(0)
.LBB0_155:
	s_andn2_b64 vcc, exec, s[2:3]
	s_cbranch_vccnz .LBB0_157
	v_or_b32_e32 v0, s8, v44
	s_lshl_b32 s0, s9, 2
	v_lshl_add_u64 v[28:29], v[20:21], 0, s[0:1]
	v_lshlrev_b32_e32 v0, 10, v0
	v_lshl_add_u64 v[28:29], v[0:1], 2, v[28:29]
	v_add_co_u32_e32 v30, vcc, 0x2000, v28
	s_lshl_b32 s0, s8, 1
	s_nop 0
	v_addc_co_u32_e32 v31, vcc, 0, v29, vcc
	v_add_co_u32_e32 v32, vcc, 0x4000, v28
	s_nop 1
	v_addc_co_u32_e32 v33, vcc, 0, v29, vcc
	v_add_co_u32_e32 v34, vcc, s18, v28
	s_nop 1
	v_addc_co_u32_e32 v35, vcc, 0, v29, vcc
	v_add_co_u32_e32 v36, vcc, 0x8000, v28
	s_nop 1
	v_addc_co_u32_e32 v37, vcc, 0, v29, vcc
	v_add_co_u32_e32 v38, vcc, 0xa000, v28
	s_nop 1
	v_addc_co_u32_e32 v39, vcc, 0, v29, vcc
	v_add_co_u32_e32 v40, vcc, s19, v28
	s_nop 1
	v_addc_co_u32_e32 v41, vcc, 0, v29, vcc
	v_add_co_u32_e32 v42, vcc, 0xe000, v28
	s_nop 1
	v_addc_co_u32_e32 v43, vcc, 0, v29, vcc
	global_load_dword v0, v[28:29], off nt
	global_load_dword v71, v[30:31], off nt
	global_load_dword v74, v[32:33], off nt
	global_load_dword v75, v[34:35], off nt
	global_load_dword v76, v[36:37], off nt
	global_load_dword v77, v[38:39], off nt
	global_load_dword v78, v[40:41], off nt
	global_load_dword v79, v[42:43], off nt
	v_add_co_u32_e32 v30, vcc, 0x10000, v28
	s_nop 1
	v_addc_co_u32_e32 v31, vcc, 0, v29, vcc
	v_add_co_u32_e32 v32, vcc, s20, v28
	s_nop 1
	v_addc_co_u32_e32 v33, vcc, 0, v29, vcc
	v_add_co_u32_e32 v34, vcc, 0x14000, v28
	s_nop 1
	v_addc_co_u32_e32 v35, vcc, 0, v29, vcc
	v_add_co_u32_e32 v36, vcc, 0x16000, v28
	s_nop 1
	v_addc_co_u32_e32 v37, vcc, 0, v29, vcc
	v_add_co_u32_e32 v38, vcc, s21, v28
	s_nop 1
	v_addc_co_u32_e32 v39, vcc, 0, v29, vcc
	v_add_co_u32_e32 v40, vcc, 0x1a000, v28
	s_nop 1
	v_addc_co_u32_e32 v41, vcc, 0, v29, vcc
	v_add_co_u32_e32 v42, vcc, 0x1c000, v28
	s_nop 1
	v_addc_co_u32_e32 v43, vcc, 0, v29, vcc
	v_add_co_u32_e32 v72, vcc, s22, v28
	s_nop 1
	v_addc_co_u32_e32 v73, vcc, 0, v29, vcc
	global_load_dword v80, v[30:31], off nt
	global_load_dword v81, v[32:33], off nt
	global_load_dword v82, v[34:35], off nt
	global_load_dword v83, v[36:37], off nt
	global_load_dword v84, v[38:39], off nt
	global_load_dword v85, v[40:41], off nt
; #define LAS __attribute__((address_space(3)))
; __device__ __forceinline__ unsigned pk2(float lo, float hi) { f32x2_t v = {lo, hi}; bf16x2_t b = __builtin_convertvector(v, bf16x2_t); return __builtin_bit_cast(unsigned, b); }
; __device__ __forceinline__ void transpose_item(const float* W, int ldw, int k0, int srcn0, bf16_t* WT, int ldk, int dstrow0, int dstk0, const float* ksc, LAS float* scr, int lane) {
;     float tv[32];
; #pragma unroll
;     for (int i = 0; i < 32; ++i) { const int kk = 2 * i + (lane >> 5); tv[i] = 0.f;
;         if (srcn0 >= 0) { tv[i] = __builtin_nontemporal_load(W + (size_t)(k0 + kk) * ldw + srcn0 + (lane & 31)); } }
; #pragma unroll
;     for (int i = 0; i < 32; ++i) { const int kk = 2 * i + (lane >> 5); float v = tv[i]; if (srcn0 >= 0 && ksc) v *= ksc[k0 + kk];
;         scr[kk * 33 + (lane & 31)] = v; }
;     asm volatile("s_waitcnt lgkmcnt(0)" ::: "memory");
;     const int c = lane & 7;
; #pragma unroll
;     for (int j = 0; j < 4; ++j) { const int n = (lane >> 3) + 8 * j; const LAS float* s = scr + (8 * c) * 33 + n;
;         u32x4 o; o.x = pk2(s[0 * 33], s[1 * 33]); o.y = pk2(s[2 * 33], s[3 * 33]); o.z = pk2(s[4 * 33], s[5 * 33]); o.w = pk2(s[6 * 33], s[7 * 33]);
;         *(u32x4*)(WT + (size_t)(dstrow0 + n) * ldk + dstk0 + 8 * c) = o; }
;     asm volatile("s_waitcnt lgkmcnt(0)" ::: "memory");
	global_load_dword v86, v[42:43], off nt
	global_load_dword v87, v[72:73], off nt
	v_add_co_u32_e32 v30, vcc, 0x20000, v28
	s_nop 1
	v_addc_co_u32_e32 v31, vcc, 0, v29, vcc
	v_add_co_u32_e32 v32, vcc, 0x22000, v28
	s_nop 1
	v_addc_co_u32_e32 v33, vcc, 0, v29, vcc
	v_add_co_u32_e32 v34, vcc, s23, v28
	s_nop 1
	v_addc_co_u32_e32 v35, vcc, 0, v29, vcc
	v_add_co_u32_e32 v36, vcc, 0x26000, v28
	s_nop 1
	v_addc_co_u32_e32 v37, vcc, 0, v29, vcc
	v_add_co_u32_e32 v38, vcc, 0x28000, v28
	s_nop 1
	v_addc_co_u32_e32 v39, vcc, 0, v29, vcc
	v_add_co_u32_e32 v40, vcc, s24, v28
	s_nop 1
	v_addc_co_u32_e32 v41, vcc, 0, v29, vcc
	v_add_co_u32_e32 v42, vcc, 0x2c000, v28
	s_nop 1
	v_addc_co_u32_e32 v43, vcc, 0, v29, vcc
	v_add_co_u32_e32 v72, vcc, 0x2e000, v28
	s_nop 1
	v_addc_co_u32_e32 v73, vcc, 0, v29, vcc
	global_load_dword v88, v[30:31], off nt
	global_load_dword v89, v[32:33], off nt
	global_load_dword v90, v[34:35], off nt
	global_load_dword v91, v[36:37], off nt
	global_load_dword v92, v[38:39], off nt
	global_load_dword v93, v[40:41], off nt
	global_load_dword v94, v[42:43], off nt
	s_nop 0
	global_load_dword v72, v[72:73], off nt
	v_add_co_u32_e32 v30, vcc, s25, v28
	s_nop 1
	v_addc_co_u32_e32 v31, vcc, 0, v29, vcc
	v_add_co_u32_e32 v32, vcc, 0x32000, v28
	s_nop 1
	v_addc_co_u32_e32 v33, vcc, 0, v29, vcc
	v_add_co_u32_e32 v34, vcc, 0x34000, v28
	s_nop 1
	v_addc_co_u32_e32 v35, vcc, 0, v29, vcc
	v_add_co_u32_e32 v36, vcc, s26, v28
	s_nop 1
	v_addc_co_u32_e32 v37, vcc, 0, v29, vcc
	v_add_co_u32_e32 v38, vcc, 0x38000, v28
	s_nop 1
	v_addc_co_u32_e32 v39, vcc, 0, v29, vcc
	v_add_co_u32_e32 v40, vcc, 0x3a000, v28
	s_nop 1
	v_addc_co_u32_e32 v41, vcc, 0, v29, vcc
	v_add_co_u32_e32 v42, vcc, s27, v28
	s_nop 1
	v_addc_co_u32_e32 v43, vcc, 0, v29, vcc
	v_add_co_u32_e32 v28, vcc, 0x3e000, v28
	s_nop 1
	v_addc_co_u32_e32 v29, vcc, 0, v29, vcc
	global_load_dword v30, v[30:31], off nt
	s_nop 0
	global_load_dword v31, v[32:33], off nt
	s_nop 0
	global_load_dword v32, v[34:35], off nt
	global_load_dword v33, v[36:37], off nt
	s_nop 0
	global_load_dword v34, v[38:39], off nt
	global_load_dword v35, v[40:41], off nt
	global_load_dword v36, v[42:43], off nt
	s_nop 0
	global_load_dword v28, v[28:29], off nt
	s_waitcnt vmcnt(30)
	ds_write2_b32 v46, v0, v71 offset1:66
	s_waitcnt vmcnt(28)
	ds_write2_b32 v46, v74, v75 offset0:132 offset1:198
	s_waitcnt vmcnt(26)
	ds_write2_b32 v64, v76, v77 offset0:8 offset1:74
	s_waitcnt vmcnt(24)
	ds_write2_b32 v64, v78, v79 offset0:140 offset1:206
	s_waitcnt vmcnt(22)
	ds_write2_b32 v65, v80, v81 offset0:16 offset1:82
	s_waitcnt vmcnt(20)
	ds_write2_b32 v65, v82, v83 offset0:148 offset1:214
	s_waitcnt vmcnt(18)
	ds_write2_b32 v66, v84, v85 offset0:24 offset1:90
	s_waitcnt vmcnt(16)
	ds_write2_b32 v66, v86, v87 offset0:156 offset1:222
	s_waitcnt vmcnt(14)
	ds_write2_b32 v67, v88, v89 offset0:32 offset1:98
	s_waitcnt vmcnt(12)
	ds_write2_b32 v67, v90, v91 offset0:164 offset1:230
	s_waitcnt vmcnt(10)
	ds_write2_b32 v68, v92, v93 offset0:40 offset1:106
	s_waitcnt vmcnt(8)
	ds_write2_b32 v68, v94, v72 offset0:172 offset1:238
	s_waitcnt vmcnt(6)
	ds_write2_b32 v69, v30, v31 offset0:48 offset1:114
	s_waitcnt vmcnt(4)
	ds_write2_b32 v69, v32, v33 offset0:180 offset1:246
	s_waitcnt vmcnt(2)
	ds_write2_b32 v70, v34, v35 offset0:56 offset1:122
	s_waitcnt vmcnt(0)
	ds_write2_b32 v70, v36, v28 offset0:188 offset1:254
	s_waitcnt lgkmcnt(0)
	ds_read2_b32 v[32:33], v48 offset0:33 offset1:41
	ds_read2_b32 v[34:35], v48 offset1:8
	ds_read2_b32 v[36:37], v48 offset0:66 offset1:74
	ds_read2_b32 v[38:39], v48 offset0:99 offset1:107
	ds_read2_b32 v[40:41], v48 offset0:132 offset1:140
	ds_read2_b32 v[42:43], v48 offset0:165 offset1:173
	ds_read2_b32 v[72:73], v48 offset0:198 offset1:206
	ds_read2_b32 v[74:75], v48 offset0:231 offset1:239
	v_lshl_add_u64 v[76:77], v[8:9], 0, s[0:1]
	v_lshlrev_b32_e32 v0, 12, v27
	s_waitcnt lgkmcnt(6)
	v_cvt_pk_bf16_f32 v28, v34, v32
	s_waitcnt lgkmcnt(4)
	v_cvt_pk_bf16_f32 v29, v36, v38
	s_waitcnt lgkmcnt(2)
	v_cvt_pk_bf16_f32 v30, v40, v42
	s_waitcnt lgkmcnt(0)
	v_cvt_pk_bf16_f32 v31, v72, v74
	v_lshl_add_u64 v[78:79], v[76:77], 0, v[0:1]
	global_store_dwordx4 v[78:79], v[28:31], off sc0 sc1
	v_lshlrev_b32_e32 v0, 12, v26
	v_lshl_add_u64 v[26:27], v[76:77], 0, v[0:1]
	v_cvt_pk_bf16_f32 v28, v35, v33
	v_cvt_pk_bf16_f32 v29, v37, v39
	v_cvt_pk_bf16_f32 v30, v41, v43
	v_cvt_pk_bf16_f32 v31, v73, v75
	ds_read2_b32 v[32:33], v48 offset0:49 offset1:57
	ds_read2_b32 v[34:35], v48 offset0:16 offset1:24
	ds_read2_b32 v[36:37], v48 offset0:82 offset1:90
	ds_read2_b32 v[38:39], v48 offset0:115 offset1:123
	ds_read2_b32 v[40:41], v48 offset0:148 offset1:156
	ds_read2_b32 v[42:43], v48 offset0:181 offset1:189
	ds_read2_b32 v[72:73], v48 offset0:214 offset1:222
	ds_read2_b32 v[74:75], v48 offset0:247 offset1:255
	v_lshlrev_b32_e32 v0, 12, v25
	global_store_dwordx4 v[26:27], v[28:31], off sc0 sc1
	s_waitcnt lgkmcnt(6)
	v_cvt_pk_bf16_f32 v26, v34, v32
	s_waitcnt lgkmcnt(4)
	v_cvt_pk_bf16_f32 v27, v36, v38
	s_waitcnt lgkmcnt(2)
	v_cvt_pk_bf16_f32 v28, v40, v42
	s_waitcnt lgkmcnt(0)
	v_cvt_pk_bf16_f32 v29, v72, v74
	v_lshl_add_u64 v[30:31], v[76:77], 0, v[0:1]
	v_lshlrev_b32_e32 v0, 12, v24
	global_store_dwordx4 v[30:31], v[26:29], off sc0 sc1
	v_lshl_add_u64 v[24:25], v[76:77], 0, v[0:1]
	s_nop 0
	v_cvt_pk_bf16_f32 v26, v35, v33
	v_cvt_pk_bf16_f32 v27, v37, v39
	v_cvt_pk_bf16_f32 v28, v41, v43
	v_cvt_pk_bf16_f32 v29, v73, v75
	global_store_dwordx4 v[24:25], v[26:29], off sc0 sc1
	s_waitcnt lgkmcnt(0)

; __device__ __forceinline__ void phase1(const Ptrs& P, int G) {
;     ...
;     if (tid == 0) {
;         unsigned* cnt = (unsigned*)(P.ws + WS_BAR) + 3520; const unsigned want = G < 96 ? (unsigned)G : 96u; unsigned sp = 0;
;         while (__hip_atomic_load(cnt, __ATOMIC_RELAXED, __HIP_MEMORY_SCOPE_AGENT) < want) { __builtin_amdgcn_s_sleep(2); if (++sp > (1u << 22)) break; }
;         __builtin_amdgcn_fence(__ATOMIC_ACQUIRE, "agent"); asm volatile("s_waitcnt vmcnt(0)" ::: "memory");
;     }
;     __syncthreads();
.Lcen_done:
	v_mov_b32_e32 v2, 0x24054
	v_mov_b32_e32 v3, s98
	ds_write_b32 v2, v3
	s_cmp_lg_u32 s98, 0
	s_cbranch_scc1 .Lcen_nopub
	v_mov_b32_e32 v2, 0x73928
	v_mov_b32_e32 v3, 1
	global_atomic_add v2, v3, s[90:91]

; __device__ __forceinline__ void phase1(const Ptrs& P, int G) {
;     ...
;         unsigned* cnt = (unsigned*)(P.ws + WS_BAR) + 3520; const unsigned want = G < 96 ? (unsigned)G : 96u; unsigned sp = 0;
;         while (__hip_atomic_load(cnt, __ATOMIC_RELAXED, __HIP_MEMORY_SCOPE_AGENT) < want) { __builtin_amdgcn_s_sleep(2); if (++sp > (1u << 22)) break; }
;         __builtin_amdgcn_fence(__ATOMIC_ACQUIRE, "agent"); asm volatile("s_waitcnt vmcnt(0)" ::: "memory");
.Lm5_spin:
	global_load_dword v246, v245, s[90:91] sc1
	v_add_u32_e32 v247, 1, v247
	s_waitcnt vmcnt(0)
	v_cmp_le_u32_e32 vcc, 0x80, v246
	s_cbranch_vccnz .Lm5_done
	v_cmp_gt_u32_e32 vcc, 0x8000, v247
	s_cbranch_vccnz .Lm5_spin

; __device__ __forceinline__ unsigned xb_ld(unsigned* p)              { return __hip_atomic_load(p, __ATOMIC_RELAXED, __HIP_MEMORY_SCOPE_AGENT); }
; #define XB_SPIN(cond, bar) do { unsigned _sp = 0; while (cond) { __builtin_amdgcn_s_sleep(1); \
;     if ((++_sp & 255u) == 0u) { if (xb_ld(&(bar)[XB_TMO])) break; if (_sp > XB_SPIN_CAP) { atomicAdd(&(bar)[XB_TMO], 1u); break; } } } } while (0)
; __device__ __forceinline__ void xcd_barrier(const XcdBarrier& b) {
;     ...
;             XB_SPIN(xb_ld(&bar[XB_XGEN(b.x)]) == gen, bar);
;             __builtin_amdgcn_fence(__ATOMIC_ACQUIRE, "agent");
;             asm volatile("s_waitcnt vmcnt(0)" ::: "memory");
.Lfb_spin_6:
	global_load_dword v1, v0, s[4:5] offset:1088 sc1
	v_add_u32_e32 v2, 1, v2
	s_waitcnt vmcnt(0)
	v_cmp_le_u32_e32 vcc, 160, v1
	s_cbranch_vccnz .Lfb_done_6
	v_cmp_gt_u32_e32 vcc, 0x8000, v2
	s_cbranch_vccnz .Lfb_spin_6
.Lfb_done_6:
	buffer_inv sc0
	s_waitcnt vmcnt(0)
	s_branch .LBB0_1373
